# attention loop: LDS staging writes interleaved with the next chunk's row loads, addresses formed before the vmcnt wait
# baseline (speedup 1.0000x reference)
.LBB0_510:
	v_add_u32_e32 v197, 1, v197
	v_lshl_add_u32 v227, v197, 7, v225
	ds_read_b128 v[234:237], v227
	ds_read_b128 v[238:241], v227 offset:16
	ds_read_b128 v[242:245], v227 offset:32
	ds_read_b128 v[246:249], v227 offset:48
	v_cmp_ge_u32_e64 s[46:47], v197, v177
	s_waitcnt lgkmcnt(0)
	v_lshl_add_u32 v234, v234, 9, v224
	v_lshl_add_u32 v235, v235, 9, v224
	v_lshl_add_u32 v236, v236, 9, v224
	v_lshl_add_u32 v237, v237, 9, v224
	v_lshl_add_u32 v238, v238, 9, v224
	v_lshl_add_u32 v239, v239, 9, v224
	v_lshl_add_u32 v240, v240, 9, v224
	v_lshl_add_u32 v241, v241, 9, v224
	v_lshl_add_u32 v242, v242, 9, v224
	v_lshl_add_u32 v243, v243, 9, v224
	v_lshl_add_u32 v244, v244, 9, v224
	v_lshl_add_u32 v245, v245, 9, v224
	v_lshl_add_u32 v246, v246, 9, v224
	v_lshl_add_u32 v247, v247, 9, v224
	v_lshl_add_u32 v248, v248, 9, v224
	v_lshl_add_u32 v249, v249, 9, v224
	s_cmp_lg_u64 s[46:47], 0
	s_waitcnt vmcnt(0)
	s_cbranch_scc1 .Latt_last
	ds_write_b128 v226, v[96:99]
	global_load_dwordx4 v[96:99], v234, s[100:101]
	ds_write_b128 v226, v[100:103] offset:544
	global_load_dwordx4 v[100:103], v235, s[100:101]
	ds_write_b128 v226, v[104:107] offset:1088
	global_load_dwordx4 v[104:107], v236, s[100:101]
	ds_write_b128 v226, v[108:111] offset:1632
	global_load_dwordx4 v[108:111], v237, s[100:101]
	ds_write_b128 v226, v[112:115] offset:2176
	global_load_dwordx4 v[112:115], v238, s[100:101]
	ds_write_b128 v226, v[116:119] offset:2720
	global_load_dwordx4 v[116:119], v239, s[100:101]
	ds_write_b128 v226, v[120:123] offset:3264
	global_load_dwordx4 v[120:123], v240, s[100:101]
	ds_write_b128 v226, v[124:127] offset:3808
	global_load_dwordx4 v[124:127], v241, s[100:101]
	ds_write_b128 v226, v[128:131] offset:4352
	global_load_dwordx4 v[128:131], v242, s[100:101]
	ds_write_b128 v226, v[132:135] offset:4896
	global_load_dwordx4 v[132:135], v243, s[100:101]
	ds_write_b128 v226, v[136:139] offset:5440
	global_load_dwordx4 v[136:139], v244, s[100:101]
	ds_write_b128 v226, v[140:143] offset:5984
	global_load_dwordx4 v[140:143], v245, s[100:101]
	ds_write_b128 v226, v[144:147] offset:6528
	global_load_dwordx4 v[144:147], v246, s[100:101]
	ds_write_b128 v226, v[148:151] offset:7072
	global_load_dwordx4 v[148:151], v247, s[100:101]
	ds_write_b128 v226, v[152:155] offset:7616
	global_load_dwordx4 v[152:155], v248, s[100:101]
	ds_write_b128 v226, v[156:159] offset:8160
	global_load_dwordx4 v[156:159], v249, s[100:101]
	s_branch .Latt_nold
.Latt_last:
	ds_write_b128 v226, v[96:99]
	ds_write_b128 v226, v[100:103] offset:544
	ds_write_b128 v226, v[104:107] offset:1088
	ds_write_b128 v226, v[108:111] offset:1632
	ds_write_b128 v226, v[112:115] offset:2176
	ds_write_b128 v226, v[116:119] offset:2720
	ds_write_b128 v226, v[120:123] offset:3264
	ds_write_b128 v226, v[124:127] offset:3808
	ds_write_b128 v226, v[128:131] offset:4352
	ds_write_b128 v226, v[132:135] offset:4896
	ds_write_b128 v226, v[136:139] offset:5440
	ds_write_b128 v226, v[140:143] offset:5984
	ds_write_b128 v226, v[144:147] offset:6528
	ds_write_b128 v226, v[148:151] offset:7072
	ds_write_b128 v226, v[152:155] offset:7616
	ds_write_b128 v226, v[156:159] offset:8160
